# GLA: KD, S-state and A-matrix tiles stored transposed in LDS so 16 ds_write_b16 become 4 ds_write_b64 (packed cvt), operand reads switched between b128 and tr reads accordingly
# speedup vs baseline: 1.0156x; 1.0035x over previous
; #define LAS __attribute__((address_space(3)))
; __device__ __forceinline__ unsigned cvtpk(float lo, float hi) { f32x2 v = {lo, hi}; bf16x2_t b = __builtin_convertvector(v, bf16x2_t); return __builtin_bit_cast(unsigned, b); }
; __device__ __forceinline__ void gla_unit(LAS char* lds0, int b, int h, int dvh, bf16_t* Z, bf16_t* OT, const float* afw, const float* afb, const float* abw, const float* abb, bool dry) {
;     int tid = threadIdx.x; asm volatile("" : "+v"(tid)); const int lane = tid & 63, r32 = lane & 31, hi = lane >> 5; const int wid = __builtin_amdgcn_readfirstlane(tid >> 6);
;     const int dir = wid >> 2, wg = wid & 3, tg = tid & 255;
;     LAS char* lds = lds0 + dir * G_GROUP;
;     const int g16 = (lane >> 4) & 1, q4 = (lane & 15) >> 2, p4 = lane & 3;
;     const int I = wg >> 1, J = wg & 1;
;     const float* w2 = dir ? abw : afw; const float* bb = dir ? abb : afb;
;     bf16x8 w2b;
;     { u32x4 t; t.x = cvtpk(w2[(8 * hi + 0) * 256 + h * 64 + 32 * J + r32], w2[(8 * hi + 1) * 256 + h * 64 + 32 * J + r32]);
;       t.y = cvtpk(w2[(8 * hi + 2) * 256 + h * 64 + 32 * J + r32], w2[(8 * hi + 3) * 256 + h * 64 + 32 * J + r32]);
;       t.z = cvtpk(w2[(8 * hi + 4) * 256 + h * 64 + 32 * J + r32], w2[(8 * hi + 5) * 256 + h * 64 + 32 * J + r32]);
;       t.w = cvtpk(w2[(8 * hi + 6) * 256 + h * 64 + 32 * J + r32], w2[(8 * hi + 7) * 256 + h * 64 + 32 * J + r32]);
;       w2b = __builtin_bit_cast(bf16x8, t); }
;     const float bias = bb[h * 64 + 32 * J + r32];
;     const int zcol_a = dir ? ZAB : ZAF;
;     f32x16 S = {};
;     for (int i = tg; i < GARR / 4; i += 256) ((LAS unsigned*)(lds + G_SB))[i] = 0u;
;     u32x4 pq0, pq1, pk0, pk1, pv0, pv1; u32x2 pa;
;     const int lr = tg >> 3, lc = tg & 7, ar = tg >> 2, ac = tg & 3;
;     ...
;     GLA_PREFETCH(0);
.LBB0_401:
	v_mov_b32_e32 v6, v182
	s_bfe_u32 s8, s97, 0x20001
	v_readfirstlane_b32 s28, v6
	s_lshr_b32 s0, s28, 8
	s_mul_i32 s0, s0, 0x10a00
	s_add_i32 s76, s0, 0
	s_bfe_u32 s42, s28, 0x10006
	s_cmpk_lt_u32 s28, 0x100
	s_cselect_b64 s[0:1], -1, 0
	s_cmpk_gt_u32 s28, 0xff
	v_readlane_b32 s52, v254, 59
	s_cselect_b64 s[16:17], -1, 0
	s_and_b64 s[2:3], s[0:1], exec
	v_readlane_b32 s54, v254, 61
	v_readlane_b32 s58, v255, 1
	v_readlane_b32 s55, v254, 62
	v_readlane_b32 s59, v255, 2
	s_cselect_b32 s2, s54, s58
	s_cselect_b32 s3, s55, s59
	s_add_u32 s2, s2, s94
	s_addc_u32 s3, s3, s95
	v_readlane_b32 s56, v254, 63
	s_and_b64 s[14:15], s[0:1], exec
	v_readlane_b32 s44, v254, 55
	v_readlane_b32 s57, v255, 0
	v_readlane_b32 s45, v254, 56
	s_cselect_b32 s15, s56, s44
	v_readlane_b32 s24, v255, 36
	v_bfe_u32 v16, v6, 3, 5
	s_cselect_b32 s14, s57, s45
	v_readlane_b32 s25, v255, 37
	s_add_u32 s24, s15, s24
	v_and_b32_e32 v14, 31, v6
	v_bfe_u32 v15, v6, 5, 1
	v_xor_b32_e32 v0, 63, v16
	s_addc_u32 s25, s14, s25
	s_lshl_b32 s43, s42, 5
	v_cndmask_b32_e64 v114, v0, v16, s[0:1]
	v_lshlrev_b32_e32 v0, 11, v15
	s_lshl_b32 s77, s8, 6
	v_or_b32_e32 v18, s43, v14
	v_or3_b32 v0, v0, s77, v18
	v_lshlrev_b32_e32 v0, 2, v0
	v_lshl_add_u64 v[2:3], s[2:3], 0, v[0:1]
	global_load_dword v17, v0, s[2:3]
	global_load_dword v19, v0, s[2:3] offset:1024
	global_load_dword v21, v0, s[2:3] offset:2048
	s_nop 0
	global_load_dword v0, v0, s[2:3] offset:3072
	s_movk_i32 s2, 0x1000
	v_add_co_u32_e32 v2, vcc, s2, v2
	s_ashr_i32 s2, s97, 3
	s_nop 0
	v_addc_co_u32_e32 v3, vcc, 0, v3, vcc
	s_lshr_b32 s40, s28, 7
	s_bfe_u32 s84, s28, 0x10007
	global_load_dword v22, v[2:3], off
	global_load_dword v23, v[2:3], off offset:1024
	global_load_dword v24, v[2:3], off offset:2048
	s_nop 0
	global_load_dword v3, v[2:3], off offset:3072
	v_and_b32_e32 v2, 0xff, v6
	s_and_b64 s[14:15], s[0:1], exec
	v_lshrrev_b32_e32 v25, 5, v6
	v_bfe_u32 v26, v6, 2, 2
	v_and_b32_e32 v27, 16, v6
	v_and_b32_e32 v28, 3, v6
	v_and_b32_e32 v7, 7, v6
	v_bfe_u32 v29, v6, 2, 6
	v_xor_b32_e32 v6, 31, v16
	v_or_b32_e32 v8, 32, v16
	v_lshl_add_u32 v2, v2, 2, s76
	s_mul_hi_i32 s14, s2, 0x900
	s_mul_i32 s15, s2, 0x900
	s_movk_i32 s2, 0x380
	s_cselect_b32 s34, 0, 0xc0
	ds_write2st64_b32 v2, v1, v1 offset0:180 offset1:184
	ds_write2st64_b32 v2, v1, v1 offset0:188 offset1:192
	ds_write2st64_b32 v2, v1, v1 offset0:196 offset1:200
	ds_write2st64_b32 v2, v1, v1 offset0:204 offset1:208
	ds_write_b32 v2, v1 offset:54272
	v_cndmask_b32_e64 v118, v6, v8, s[0:1]
	v_or_b32_e32 v2, s77, v18
	s_cselect_b32 s28, s2, 0x3a0
	s_or_b32 s34, s34, s15
	v_mov_b64_e32 v[4:5], s[88:89]
	v_lshlrev_b32_e32 v2, 2, v2
	v_or_b32_e32 v6, s34, v114
	v_or_b32_e32 v8, s34, v118
	v_lshlrev_b32_e32 v20, 3, v7
	v_lshlrev_b32_e32 v116, 4, v7
	global_load_dword v2, v2, s[24:25]
	v_mad_u64_u32 v[6:7], s[24:25], v6, s13, v[4:5]
	v_mad_u64_u32 v[8:9], s[24:25], v8, s13, v[4:5]
	s_mov_b32 s3, s9
	s_lshl_b32 s2, s8, 7
	v_mad_i32_i24 v7, s14, v204, v7
	v_mad_i32_i24 v9, s14, v204, v9
	v_lshl_add_u64 v[10:11], v[6:7], 0, s[2:3]
	v_lshl_add_u64 v[12:13], v[8:9], 0, s[2:3]
	s_lshl_b32 s3, s97, 6
	s_lshl_b32 s8, s8, 8
	s_and_b32 s3, s3, 64
	s_mov_b32 s29, 0
	v_lshl_add_u64 v[6:7], v[6:7], 0, s[8:9]
	s_lshl_b32 s24, s3, 1
	s_mov_b32 s25, s9
	v_mov_b32_e32 v117, v1
	v_lshl_add_u64 v[6:7], v[6:7], 0, s[24:25]
	v_lshl_add_u64 v[8:9], v[8:9], 0, s[8:9]
	v_lshl_add_u64 v[10:11], v[10:11], 0, v[116:117]
	v_lshl_add_u64 v[12:13], v[12:13], 0, v[116:117]
	v_lshl_add_u64 v[6:7], v[6:7], 0, v[116:117]
	v_lshl_add_u64 v[8:9], v[8:9], 0, s[24:25]
	global_load_dwordx4 v[70:73], v[10:11], off offset:2048
	global_load_dwordx4 v[74:77], v[10:11], off offset:2560
	global_load_dwordx4 v[78:81], v[12:13], off offset:2048
	global_load_dwordx4 v[82:85], v[12:13], off offset:2560
	v_lshl_add_u64 v[8:9], v[8:9], 0, v[116:117]
	global_load_dwordx4 v[86:89], v[6:7], off offset:3072
	global_load_dwordx4 v[90:93], v[8:9], off offset:3072
	v_and_b32_e32 v6, 64, v203
	v_add_u32_e32 v6, 64, v6
	v_lshlrev_b32_e32 v30, 3, v15
	v_mov_b32_e32 v31, s76
	s_movk_i32 s44, 0x90
	v_mad_u32_u24 v136, v18, s44, v31
	v_or_b32_e32 v44, v30, v26
	v_readlane_b32 s46, v254, 57
	v_readlane_b32 s47, v254, 58
	v_mul_u32_u24_e32 v154, 0x90, v44
	v_or_b32_e32 v44, 16, v30
	v_or_b32_e32 v46, 32, v30
	v_or_b32_e32 v30, 48, v30
	v_readlane_b32 s53, v254, 60
	v_mad_u32_u24 v115, v16, s44, v31
	s_waitcnt vmcnt(0)
; #define LAS __attribute__((address_space(3)))
; __device__ __forceinline__ unsigned cvtpk(float lo, float hi) { f32x2 v = {lo, hi}; bf16x2_t b = __builtin_convertvector(v, bf16x2_t); return __builtin_bit_cast(unsigned, b); }
; __device__ __forceinline__ void gla_unit(LAS char* lds0, int b, int h, int dvh, bf16_t* Z, bf16_t* OT, const float* afw, const float* afb, const float* abw, const float* abb, bool dry) {
;     int tid = threadIdx.x; asm volatile("" : "+v"(tid)); const int lane = tid & 63, r32 = lane & 31, hi = lane >> 5; const int wid = __builtin_amdgcn_readfirstlane(tid >> 6);
;     const int dir = wid >> 2, wg = wid & 3, tg = tid & 255;
;     LAS char* lds = lds0 + dir * G_GROUP;
;     const int g16 = (lane >> 4) & 1, q4 = (lane & 15) >> 2, p4 = lane & 3;
;     const int I = wg >> 1, J = wg & 1;
;     const float* w2 = dir ? abw : afw; const float* bb = dir ? abb : afb;
;     bf16x8 w2b;
;     { u32x4 t; t.x = cvtpk(w2[(8 * hi + 0) * 256 + h * 64 + 32 * J + r32], w2[(8 * hi + 1) * 256 + h * 64 + 32 * J + r32]);
;       t.y = cvtpk(w2[(8 * hi + 2) * 256 + h * 64 + 32 * J + r32], w2[(8 * hi + 3) * 256 + h * 64 + 32 * J + r32]);
;       t.z = cvtpk(w2[(8 * hi + 4) * 256 + h * 64 + 32 * J + r32], w2[(8 * hi + 5) * 256 + h * 64 + 32 * J + r32]);
;       t.w = cvtpk(w2[(8 * hi + 6) * 256 + h * 64 + 32 * J + r32], w2[(8 * hi + 7) * 256 + h * 64 + 32 * J + r32]);
;       w2b = __builtin_bit_cast(bf16x8, t); }
;     const float bias = bb[h * 64 + 32 * J + r32];
;     const int zcol_a = dir ? ZAB : ZAF;
;     f32x16 S = {};
;     for (int i = tg; i < GARR / 4; i += 256) ((LAS unsigned*)(lds + G_SB))[i] = 0u;
;     u32x4 pq0, pq1, pk0, pk1, pv0, pv1; u32x2 pa;
;     const int lr = tg >> 3, lc = tg & 7, ar = tg >> 2, ac = tg & 3;
	v_cvt_pk_bf16_f32 v67, v21, v0
	v_xor_b32_e32 v0, 63, v29
	v_cndmask_b32_e64 v120, v0, v29, s[0:1]
	v_or_b32_e32 v0, s34, v120
	v_mad_u64_u32 v[4:5], s[34:35], v0, s13, v[4:5]
	v_mad_i32_i24 v5, s14, v204, v5
	v_lshl_add_u64 v[4:5], v[4:5], 0, s[28:29]
	v_lshlrev_b32_e32 v0, 3, v28
	v_lshl_add_u64 v[4:5], v[4:5], 0, v[0:1]
	global_load_dwordx2 v[126:127], v[4:5], off
	s_add_u32 s34, s88, s28
	s_addc_u32 s35, s89, 0
	v_lshl_add_u64 v[122:123], s[34:35], 0, v[0:1]
	v_readlane_b32 s34, v252, 21
	v_readlane_b32 s35, v252, 22
	s_add_u32 s8, s34, s8
	s_addc_u32 s25, s35, 0
	s_add_u32 s24, s8, s24
	s_addc_u32 s25, s25, 0
	v_lshl_add_u64 v[124:125], s[24:25], 0, v[116:117]
	s_add_i32 s24, s76, 0x10500
	s_lshl_b32 s28, s42, 7
	v_xor_b32_e32 v5, 32, v203
	s_lshl_b32 s25, s84, 8
	s_add_i32 s28, s24, s28
	s_lshl_b32 s8, s84, 5
	v_cmp_lt_i32_e32 vcc, v5, v6
	s_add_i32 s25, s28, s25
	v_cvt_pk_bf16_f32 v68, v22, v23
	v_cndmask_b32_e32 v5, v203, v5, vcc
	v_lshlrev_b32_e32 v6, 2, v18
	s_cmp_eq_u32 s84, 0
	v_lshl_or_b32 v23, v15, 2, s8
	v_lshl_add_u32 v21, v29, 5, s76
	v_lshlrev_b32_e32 v119, 2, v5
	v_lshlrev_b32_e32 v5, 2, v14
	v_add_u32_e32 v132, s24, v6
	s_cselect_b64 s[34:35], -1, 0
	s_add_i32 s24, s76, 0x10400
	v_mul_u32_u24_e32 v29, 0x48, v23
	v_cvt_pk_bf16_f32 v69, v24, v3
	v_lshlrev_b32_e32 v3, 2, v28
	v_or_b32_e32 v4, s8, v14
	v_add_u32_e32 v121, s25, v5
	v_lshlrev_b32_e32 v24, 1, v18
	s_cmp_le_u32 s42, s84
	s_movk_i32 s25, 0xff72
	v_lshlrev_b32_e32 v29, 1, v29
	v_lshl_add_u32 v22, v4, 5, s76
	v_lshlrev_b32_e32 v117, 4, v15
	v_add_u32_e32 v133, s28, v5
	v_bitop3_b32 v5, s40, 1, v25 bitop3:0xc8
	s_cselect_b64 s[78:79], -1, 0
	v_mad_u32_u24 v135, v4, s44, v31
	v_or3_b32 v4, v3, v27, s43
	v_mad_i32_i24 v25, v18, s25, v136
	v_lshl_add_u32 v238, v23, 1, v136
	v_add_u32_e32 v239, v136, v117
	s_lshl_b32 s25, s42, 6
	v_or3_b32 v3, v27, s8, v3
	v_add3_u32 v138, s76, v24, v29
	v_or_b32_e32 v29, 2, v23
	s_add_i32 s8, s76, 0x10420
	v_lshl_add_u32 v137, v4, 1, s76
	s_add_i32 s25, s76, s25
	v_lshl_add_u32 v27, v3, 1, s76
	v_or_b32_e32 v24, 1, v23
	v_or_b32_e32 v31, 3, v23
	v_or_b32_e32 v32, 8, v23
	v_or_b32_e32 v33, 9, v23
	v_or_b32_e32 v34, 10, v23
	v_or_b32_e32 v35, 11, v23
	v_or_b32_e32 v36, 16, v23
	v_or_b32_e32 v37, 17, v23
	v_or_b32_e32 v38, 18, v23
	v_or_b32_e32 v39, 19, v23
	v_or_b32_e32 v40, 24, v23
	v_or_b32_e32 v41, 25, v23
	v_or_b32_e32 v42, 26, v23
	v_or_b32_e32 v43, 27, v23
	v_lshlrev_b32_e32 v45, 1, v44
	v_or_b32_e32 v44, v44, v26
	v_lshlrev_b32_e32 v47, 1, v46
	v_or_b32_e32 v46, v46, v26
	v_or_b32_e32 v26, v30, v26
	v_cmp_lt_u32_e64 s[46:47], v29, v18
	v_add_u32_e32 v29, s8, v117
	s_add_i32 s8, s76, 0x10440
	s_add_i32 s76, s76, 0x10460
	v_cvt_pk_bf16_f32 v66, v17, v19
	v_add_u32_e32 v19, 0x1200, v115
	v_lshl_add_u32 v28, v14, 1, s25
	v_mul_u32_u24_e32 v44, 0x90, v44
	v_mul_u32_u24_e32 v46, 0x90, v46
	v_lshlrev_b32_e32 v48, 1, v30
	v_mul_u32_u24_e32 v26, 0x90, v26
	v_cmp_lt_u32_e64 s[42:43], v23, v18
	v_mul_u32_u24_e32 v23, 0x90, v23
	v_cmp_lt_u32_e64 s[44:45], v24, v18
	v_cmp_lt_u32_e64 s[50:51], v31, v18
	v_cmp_lt_u32_e64 s[52:53], v32, v18
	v_cmp_lt_u32_e64 s[54:55], v33, v18
	v_cmp_lt_u32_e64 s[56:57], v34, v18
	v_cmp_lt_u32_e64 s[58:59], v35, v18
	v_cmp_lt_u32_e64 s[60:61], v36, v18
	v_cmp_lt_u32_e64 s[62:63], v37, v18
	v_cmp_lt_u32_e64 s[64:65], v38, v18
	v_cmp_lt_u32_e64 s[66:67], v39, v18
	v_cmp_lt_u32_e64 s[68:69], v40, v18
	v_cmp_lt_u32_e64 s[70:71], v41, v18
	v_cmp_lt_u32_e64 s[72:73], v42, v18
	v_cmp_lt_u32_e64 s[74:75], v43, v18
	s_lshl_b32 s25, s84, 7
	v_add_u32_e32 v24, s24, v117
	v_add_u32_e32 v30, s8, v117
	v_add_u32_e32 v31, s76, v117
	v_mov_b32_e32 v18, 0
	v_cmp_eq_u32_e64 s[38:39], 0, v15
	v_cmp_eq_u32_e64 s[40:41], 0, v5
	v_add_u32_e32 v134, s24, v6
	v_mov_b32_e32 v3, v2
	v_mov_b32_e32 v4, v2
	v_mov_b32_e32 v5, v2
	v_mov_b32_e32 v6, v2
	v_mov_b32_e32 v7, v2
	v_mov_b32_e32 v8, v2
	v_mov_b32_e32 v9, v2
	v_mov_b32_e32 v10, v2
	v_mov_b32_e32 v11, v2
	v_mov_b32_e32 v12, v2
	v_mov_b32_e32 v13, v2
	v_mov_b32_e32 v14, v2
	v_mov_b32_e32 v15, v2
	v_mov_b32_e32 v16, v2
	v_mov_b32_e32 v17, v2
	v_add_u32_e32 v139, 0x90, v138
	s_waitcnt lgkmcnt(5)
	v_add_u32_e32 v140, 0x120, v138
	v_add_u32_e32 v141, 0x1b0, v138
	v_add_u32_e32 v142, 0x480, v138
	v_add_u32_e32 v143, 0x510, v138
	v_add_u32_e32 v144, 0x5a0, v138
	v_add_u32_e32 v145, 0x630, v138
	v_add_u32_e32 v146, 0x900, v138
	v_add_u32_e32 v147, 0x990, v138
	v_add_u32_e32 v148, 0xa20, v138
	v_add_u32_e32 v149, 0xab0, v138
	v_add_u32_e32 v150, 0xd80, v138
	v_add_u32_e32 v151, 0xe10, v138
	v_add_u32_e32 v152, 0xea0, v138
	v_add_u32_e32 v153, 0xf30, v138
	v_add_u32_e32 v155, v21, v0
	s_lshl_b32 s8, s77, 1
	v_lshlrev_b32_e32 v0, 1, v20
	s_lshl_b32 s24, s2, 1
	s_lshl_b32 s84, s3, 1
	v_add_u32_e32 v156, v22, v117
	v_add_u32_e32 v157, v137, v44
	v_add_u32_e32 v158, v137, v46
	v_add_u32_e32 v159, v137, v26
	v_add_u32_e32 v160, v25, v23
	v_add_u32_e32 v161, v28, v23
	v_add_u32_e32 v162, s25, v24
	v_add_u32_e32 v163, s25, v29
	v_add_u32_e32 v164, s25, v30
	v_add_u32_e32 v165, s25, v31
	v_add_u32_e32 v166, v27, v154
	v_add_u32_e32 v167, v19, v116
	v_add_u32_e32 v168, v135, v45
	v_add_u32_e32 v169, v135, v47
	v_add_u32_e32 v170, v135, v48
	s_mov_b32 s76, s29
	v_mov_b32_e32 v19, v18
	v_mov_b32_e32 v20, v18
	v_mov_b32_e32 v21, v18
	v_mov_b32_e32 v22, v18
	v_mov_b32_e32 v23, v18
	v_mov_b32_e32 v24, v18
	v_mov_b32_e32 v25, v18
	v_mov_b32_e32 v26, v18
	v_mov_b32_e32 v27, v18
	v_mov_b32_e32 v28, v18
	v_mov_b32_e32 v29, v18
	v_mov_b32_e32 v30, v18
	v_mov_b32_e32 v31, v18
	v_mov_b32_e32 v32, v18
	v_mov_b32_e32 v33, v18
	s_branch .LBB0_403

; #define LAS __attribute__((address_space(3)))
; __device__ __forceinline__ bf16_t f2bf(float f) { return (bf16_t)(cvtpk(f, 0.f) & 0xffffu); }
; __device__ __forceinline__ float bf2f(bf16_t b) { return __uint_as_float(((unsigned)b) << 16); }
; __device__ __forceinline__ float fexp(float x) { return __builtin_amdgcn_exp2f(x * 1.4426950408889634f); }
; __device__ __forceinline__ float frcp(float x) { return __builtin_amdgcn_rcpf(x); }
; __device__ __forceinline__ int crow(int r, int hi) { return (r & 3) + 8 * (r >> 2) + 4 * hi; }
; __device__ __forceinline__ void gla_unit(LAS char* lds0, int b, int h, int dvh, bf16_t* Z, bf16_t* OT, const float* afw, const float* afb, const float* abw, const float* abb, bool dry) {
;     ...
;         if (hi == 0) ((LAS float*)(lds + G_TOT))[I * 64 + 32 * J + r32] = run;
;         asm volatile("s_waitcnt lgkmcnt(0)\n\ts_barrier" ::: "memory");
;         const float t0v = ((LAS float*)(lds + G_TOT))[32 * J + r32], t1v = ((LAS float*)(lds + G_TOT))[64 + 32 * J + r32];
;         const float pre = I ? t0v : 0.f, tot = t0v + t1v;
;         const float etot = fexp(tot);
; #pragma unroll
;         for (int r = 0; r < 16; ++r) {
;             const int ii = 32 * I + crow(r, hi), dd = 32 * J + r32; const float eb = fexp(pre + cs[r]); const float ieb = frcp(eb);
;             LAS bf16_t* qp = (LAS bf16_t*)(lds + G_Q) + ii * (GP / 2) + dd; LAS bf16_t* kp = (LAS bf16_t*)(lds + G_K) + ii * (GP / 2) + dd;
;             const float qv = bf2f(*qp), kv = bf2f(*kp);
;             *qp = f2bf(qv * eb); *kp = f2bf(kv * ieb);
;             ((LAS bf16_t*)(lds + G_KD))[ii * (GP / 2) + dd] = f2bf(kv * ieb * etot);
;         }
.LBB0_414:
	s_or_b64 exec, exec, s[76:77]
	v_add_f32_e32 v51, 0, v51
	v_cndmask_b32_e64 v51, v51, 0, s[38:39]
	v_add_f32_e32 v57, v51, v34
	v_cndmask_b32_e64 v34, v53, 0, s[38:39]
	v_add_f32_e32 v34, v34, v50
	v_add_f32_e32 v58, v51, v44
	v_add_f32_e32 v59, v51, v45
	v_add_f32_e32 v49, v51, v49
	v_add_f32_e32 v50, v37, v34
	v_add_f32_e32 v51, v42, v34
	v_add_f32_e32 v45, v43, v34
	v_add_f32_e32 v44, v41, v34
	v_cndmask_b32_e64 v34, v55, 0, s[38:39]
	v_add_f32_e32 v34, v34, v52
	v_add_f32_e32 v43, v40, v34
	v_add_f32_e32 v42, v38, v34
	v_add_f32_e32 v41, v39, v34
	v_add_f32_e32 v40, v48, v34
	s_waitcnt lgkmcnt(0)
	v_cndmask_b32_e64 v34, v56, 0, s[38:39]
	v_add_f32_e32 v34, v34, v54
	s_waitcnt lgkmcnt(0)
	s_barrier
	v_add_f32_e32 v39, v46, v34
	v_add_f32_e32 v38, v35, v34
	ds_read_b32 v35, v132
	ds_read_b32 v46, v133 offset:256
	ds_read_u16 v206, v138
	ds_read_u16 v207, v138 offset:9216
	ds_read_u16 v208, v139
	ds_read_u16 v209, v139 offset:9216
	ds_read_u16 v210, v140
	ds_read_u16 v211, v140 offset:9216
	ds_read_u16 v212, v141
	ds_read_u16 v213, v141 offset:9216
	ds_read_u16 v214, v142
	ds_read_u16 v215, v142 offset:9216
	ds_read_u16 v216, v143
	ds_read_u16 v217, v143 offset:9216
	ds_read_u16 v218, v144
	ds_read_u16 v219, v144 offset:9216
	ds_read_u16 v220, v145
	ds_read_u16 v221, v145 offset:9216
	ds_read_u16 v222, v146
	ds_read_u16 v223, v146 offset:9216
	ds_read_u16 v224, v147
	ds_read_u16 v225, v147 offset:9216
	ds_read_u16 v226, v148
	ds_read_u16 v227, v148 offset:9216
	ds_read_u16 v228, v149
	ds_read_u16 v229, v149 offset:9216
	ds_read_u16 v230, v150
	ds_read_u16 v231, v150 offset:9216
	ds_read_u16 v232, v151
	ds_read_u16 v233, v151 offset:9216
	ds_read_u16 v234, v152
	ds_read_u16 v235, v152 offset:9216
	ds_read_u16 v236, v153
	ds_read_u16 v237, v153 offset:9216
	s_waitcnt lgkmcnt(0)
	v_add_f32_e32 v36, v36, v34
	v_cndmask_b32_e64 v37, v35, 0, s[34:35]
	v_add_f32_e32 v35, v35, v46
	v_add_f32_e32 v46, v57, v37
	v_mul_f32_e32 v46, 0x3fb8aa3b, v46
	v_exp_f32_e32 v46, v46
	v_add_f32_e32 v34, v47, v34
	v_mul_f32_e32 v35, 0x3fb8aa3b, v35
	v_exp_f32_e32 v35, v35
	v_rcp_f32_e32 v47, v46
	v_lshlrev_b32_e32 v48, 16, v206
	v_mul_f32_e32 v46, v46, v48
	v_lshlrev_b32_e32 v52, 16, v207
	v_cvt_pk_bf16_f32 v46, v46, s0
	ds_write_b16 v138, v46
	v_mul_f32_e32 v46, v47, v52
	v_cvt_pk_bf16_f32 v47, v46, s0
	v_mul_f32_e32 v240, v35, v46
	v_add_f32_e32 v46, v58, v37
	v_mul_f32_e32 v46, 0x3fb8aa3b, v46
	v_exp_f32_e32 v46, v46
	ds_write_b16 v138, v47 offset:9216
	v_rcp_f32_e32 v47, v46
	v_add_f32_e32 v45, v45, v37
	v_lshlrev_b32_e32 v48, 16, v208
	v_mul_f32_e32 v46, v46, v48
	v_lshlrev_b32_e32 v52, 16, v209
	v_cvt_pk_bf16_f32 v46, v46, s0
	ds_write_b16 v139, v46
	v_mul_f32_e32 v46, v47, v52
	v_cvt_pk_bf16_f32 v47, v46, s0
	v_mul_f32_e32 v46, v35, v46
	v_cvt_pk_bf16_f32 v242, v240, v46
	v_add_f32_e32 v46, v59, v37
	v_mul_f32_e32 v46, 0x3fb8aa3b, v46
	v_exp_f32_e32 v46, v46
	ds_write_b16 v139, v47 offset:9216
	v_rcp_f32_e32 v47, v46
	v_mul_f32_e32 v45, 0x3fb8aa3b, v45
	v_lshlrev_b32_e32 v48, 16, v210
	v_mul_f32_e32 v46, v46, v48
	v_lshlrev_b32_e32 v52, 16, v211
	v_cvt_pk_bf16_f32 v46, v46, s0
	ds_write_b16 v140, v46
	v_mul_f32_e32 v46, v47, v52
	v_cvt_pk_bf16_f32 v47, v46, s0
	v_mul_f32_e32 v240, v35, v46
	v_add_f32_e32 v46, v49, v37
	v_mul_f32_e32 v46, 0x3fb8aa3b, v46
	v_exp_f32_e32 v46, v46
	ds_write_b16 v140, v47 offset:9216
	v_rcp_f32_e32 v47, v46
	v_exp_f32_e32 v45, v45
	v_lshlrev_b32_e32 v48, 16, v212
	v_mul_f32_e32 v46, v46, v48
	v_lshlrev_b32_e32 v49, 16, v213
	v_cvt_pk_bf16_f32 v46, v46, s0
	ds_write_b16 v141, v46
	v_mul_f32_e32 v46, v47, v49
	v_cvt_pk_bf16_f32 v47, v46, s0
	v_mul_f32_e32 v46, v35, v46
	v_cvt_pk_bf16_f32 v243, v240, v46
	ds_write_b64 v238, v[242:243] offset:18432
	v_add_f32_e32 v46, v50, v37
	v_mul_f32_e32 v46, 0x3fb8aa3b, v46
	v_exp_f32_e32 v46, v46
	ds_write_b16 v141, v47 offset:9216
	v_rcp_f32_e32 v47, v46
	v_add_f32_e32 v44, v44, v37
	v_lshlrev_b32_e32 v48, 16, v214
	v_mul_f32_e32 v46, v46, v48
	v_lshlrev_b32_e32 v49, 16, v215
	v_cvt_pk_bf16_f32 v46, v46, s0
	ds_write_b16 v142, v46
	v_mul_f32_e32 v46, v47, v49
	v_cvt_pk_bf16_f32 v47, v46, s0
	v_mul_f32_e32 v240, v35, v46
	v_add_f32_e32 v46, v51, v37
	v_mul_f32_e32 v46, 0x3fb8aa3b, v46
	v_exp_f32_e32 v46, v46
	ds_write_b16 v142, v47 offset:9216
	v_rcp_f32_e32 v47, v46
	v_mul_f32_e32 v44, 0x3fb8aa3b, v44
	v_lshlrev_b32_e32 v48, 16, v216
	v_mul_f32_e32 v46, v46, v48
	v_lshlrev_b32_e32 v49, 16, v217
	v_cvt_pk_bf16_f32 v46, v46, s0
	ds_write_b16 v143, v46
	v_mul_f32_e32 v46, v47, v49
	v_cvt_pk_bf16_f32 v47, v46, s0
	ds_write_b16 v143, v47 offset:9216
	v_mul_f32_e32 v46, v35, v46
	v_cvt_pk_bf16_f32 v242, v240, v46
	v_rcp_f32_e32 v46, v45
	v_lshlrev_b32_e32 v47, 16, v218
	v_mul_f32_e32 v45, v45, v47
	v_lshlrev_b32_e32 v48, 16, v219
	v_cvt_pk_bf16_f32 v45, v45, s0
	ds_write_b16 v144, v45
; #define LAS __attribute__((address_space(3)))
; __device__ __forceinline__ bf16_t f2bf(float f) { return (bf16_t)(cvtpk(f, 0.f) & 0xffffu); }
; __device__ __forceinline__ float bf2f(bf16_t b) { return __uint_as_float(((unsigned)b) << 16); }
; __device__ __forceinline__ float fexp(float x) { return __builtin_amdgcn_exp2f(x * 1.4426950408889634f); }
; __device__ __forceinline__ float frcp(float x) { return __builtin_amdgcn_rcpf(x); }
; __device__ __forceinline__ int crow(int r, int hi) { return (r & 3) + 8 * (r >> 2) + 4 * hi; }
; __device__ __forceinline__ void gla_unit(LAS char* lds0, int b, int h, int dvh, bf16_t* Z, bf16_t* OT, const float* afw, const float* afb, const float* abw, const float* abb, bool dry) {
;     ...
;         for (int r = 0; r < 16; ++r) {
;             const int ii = 32 * I + crow(r, hi), dd = 32 * J + r32; const float eb = fexp(pre + cs[r]); const float ieb = frcp(eb);
;             LAS bf16_t* qp = (LAS bf16_t*)(lds + G_Q) + ii * (GP / 2) + dd; LAS bf16_t* kp = (LAS bf16_t*)(lds + G_K) + ii * (GP / 2) + dd;
;             const float qv = bf2f(*qp), kv = bf2f(*kp);
;             *qp = f2bf(qv * eb); *kp = f2bf(kv * ieb);
;             ((LAS bf16_t*)(lds + G_KD))[ii * (GP / 2) + dd] = f2bf(kv * ieb * etot);
;         }
;         if (I == 0 && hi == 0) ((LAS float*)(lds + G_DEC))[32 * J + r32] = etot;
;         asm volatile("s_waitcnt lgkmcnt(0)\n\ts_barrier" ::: "memory");
;         f32x16 oacc = {};
;         {
;             f32x16 Ac = {};
;             if (J <= I) {
; #pragma unroll
;                 for (int k = 0; k < 4; ++k) {
;                     const bf16x8 a = *(const LAS bf16x8*)(lds + G_Q + (32 * I + r32) * GP + (16 * k + 8 * hi) * 2);
;                     const bf16x8 bq = *(const LAS bf16x8*)(lds + G_K + (32 * J + r32) * GP + (16 * k + 8 * hi) * 2);
;                     Ac = __builtin_amdgcn_mfma_f32_32x32x16_bf16(a, bq, Ac, 0, 0, 0);
;                 }
;             }
	v_mul_f32_e32 v45, v46, v48
	v_cvt_pk_bf16_f32 v46, v45, s0
	v_mul_f32_e32 v240, v35, v45
	ds_write_b16 v144, v46 offset:9216
	v_exp_f32_e32 v44, v44
	v_add_f32_e32 v43, v43, v37
	v_rcp_f32_e32 v45, v44
	v_mul_f32_e32 v43, 0x3fb8aa3b, v43
	v_lshlrev_b32_e32 v46, 16, v220
	v_mul_f32_e32 v44, v44, v46
	v_lshlrev_b32_e32 v47, 16, v221
	v_cvt_pk_bf16_f32 v44, v44, s0
	ds_write_b16 v145, v44
	v_mul_f32_e32 v44, v45, v47
	v_cvt_pk_bf16_f32 v45, v44, s0
	v_mul_f32_e32 v44, v35, v44
	v_cvt_pk_bf16_f32 v243, v240, v44
	ds_write_b16 v145, v45 offset:9216
	ds_write_b64 v238, v[242:243] offset:18448
	v_exp_f32_e32 v43, v43
	v_add_f32_e32 v42, v42, v37
	v_rcp_f32_e32 v44, v43
	v_mul_f32_e32 v42, 0x3fb8aa3b, v42
	v_lshlrev_b32_e32 v45, 16, v222
	v_mul_f32_e32 v43, v43, v45
	v_lshlrev_b32_e32 v46, 16, v223
	v_cvt_pk_bf16_f32 v43, v43, s0
	ds_write_b16 v146, v43
	v_mul_f32_e32 v43, v44, v46
	v_cvt_pk_bf16_f32 v44, v43, s0
	v_mul_f32_e32 v240, v35, v43
	ds_write_b16 v146, v44 offset:9216
	v_exp_f32_e32 v42, v42
	v_add_f32_e32 v41, v41, v37
	v_rcp_f32_e32 v43, v42
	v_mul_f32_e32 v41, 0x3fb8aa3b, v41
	v_lshlrev_b32_e32 v44, 16, v224
	v_mul_f32_e32 v42, v42, v44
	v_lshlrev_b32_e32 v45, 16, v225
	v_cvt_pk_bf16_f32 v42, v42, s0
	ds_write_b16 v147, v42
	v_mul_f32_e32 v42, v43, v45
	v_cvt_pk_bf16_f32 v43, v42, s0
	v_mul_f32_e32 v42, v35, v42
	v_cvt_pk_bf16_f32 v242, v240, v42
	ds_write_b16 v147, v43 offset:9216
	v_exp_f32_e32 v41, v41
	v_add_f32_e32 v40, v40, v37
	v_rcp_f32_e32 v42, v41
	v_mul_f32_e32 v40, 0x3fb8aa3b, v40
	v_lshlrev_b32_e32 v43, 16, v226
	v_mul_f32_e32 v41, v41, v43
	v_lshlrev_b32_e32 v44, 16, v227
	v_cvt_pk_bf16_f32 v41, v41, s0
	ds_write_b16 v148, v41
	v_mul_f32_e32 v41, v42, v44
	v_cvt_pk_bf16_f32 v42, v41, s0
	v_mul_f32_e32 v240, v35, v41
	ds_write_b16 v148, v42 offset:9216
	v_exp_f32_e32 v40, v40
	v_add_f32_e32 v39, v39, v37
	v_rcp_f32_e32 v41, v40
	v_mul_f32_e32 v39, 0x3fb8aa3b, v39
	v_lshlrev_b32_e32 v42, 16, v228
	v_mul_f32_e32 v40, v40, v42
	v_lshlrev_b32_e32 v43, 16, v229
	v_cvt_pk_bf16_f32 v40, v40, s0
	ds_write_b16 v149, v40
	v_mul_f32_e32 v40, v41, v43
	v_cvt_pk_bf16_f32 v41, v40, s0
	v_mul_f32_e32 v40, v35, v40
	v_cvt_pk_bf16_f32 v243, v240, v40
	ds_write_b16 v149, v41 offset:9216
	ds_write_b64 v238, v[242:243] offset:18464
	v_exp_f32_e32 v39, v39
	v_add_f32_e32 v38, v38, v37
	v_rcp_f32_e32 v40, v39
	v_mul_f32_e32 v38, 0x3fb8aa3b, v38
	v_lshlrev_b32_e32 v41, 16, v230
	v_mul_f32_e32 v39, v39, v41
	v_lshlrev_b32_e32 v42, 16, v231
	v_cvt_pk_bf16_f32 v39, v39, s0
	ds_write_b16 v150, v39
	v_mul_f32_e32 v39, v40, v42
	v_cvt_pk_bf16_f32 v40, v39, s0
	v_mul_f32_e32 v240, v35, v39
	ds_write_b16 v150, v40 offset:9216
	v_exp_f32_e32 v38, v38
	v_add_f32_e32 v36, v36, v37
	v_rcp_f32_e32 v39, v38
	v_mul_f32_e32 v36, 0x3fb8aa3b, v36
	v_lshlrev_b32_e32 v40, 16, v232
	v_mul_f32_e32 v38, v38, v40
	v_lshlrev_b32_e32 v41, 16, v233
	v_cvt_pk_bf16_f32 v38, v38, s0
	ds_write_b16 v151, v38
	v_mul_f32_e32 v38, v39, v41
	v_cvt_pk_bf16_f32 v39, v38, s0
	v_mul_f32_e32 v38, v35, v38
	v_cvt_pk_bf16_f32 v242, v240, v38
	ds_write_b16 v151, v39 offset:9216
	v_exp_f32_e32 v36, v36
	v_add_f32_e32 v34, v34, v37
	v_rcp_f32_e32 v38, v36
	v_mul_f32_e32 v34, 0x3fb8aa3b, v34
	v_lshlrev_b32_e32 v39, 16, v234
	v_mul_f32_e32 v36, v36, v39
	v_lshlrev_b32_e32 v40, 16, v235
	v_cvt_pk_bf16_f32 v36, v36, s0
	ds_write_b16 v152, v36
	v_mul_f32_e32 v36, v38, v40
	v_cvt_pk_bf16_f32 v38, v36, s0
	v_mul_f32_e32 v240, v35, v36
	ds_write_b16 v152, v38 offset:9216
	v_exp_f32_e32 v34, v34
	v_rcp_f32_e32 v36, v34
	v_lshlrev_b32_e32 v37, 16, v236
	v_mul_f32_e32 v34, v34, v37
	v_lshlrev_b32_e32 v38, 16, v237
	v_cvt_pk_bf16_f32 v34, v34, s0
	ds_write_b16 v153, v34
	v_mul_f32_e32 v34, v36, v38
	v_cvt_pk_bf16_f32 v36, v34, s0
	v_mul_f32_e32 v34, v35, v34
	v_cvt_pk_bf16_f32 v243, v240, v34
	ds_write_b16 v153, v36 offset:9216
	ds_write_b64 v238, v[242:243] offset:18480
	s_and_saveexec_b64 s[76:77], s[40:41]
	ds_write_b32 v134, v35
	s_or_b64 exec, exec, s[76:77]
	s_waitcnt lgkmcnt(0)
	s_barrier
	v_add_u32_e32 v172, v135, v117
	ds_read_b128 v[50:53], v172
	s_mov_b64 s[76:77], -1
	s_and_b64 vcc, exec, s[78:79]
	s_cbranch_vccz .LBB0_418
	v_add_u32_e32 v58, v136, v117
	ds_read_b128 v[34:37], v58 offset:9216
	ds_read_b128 v[54:57], v58 offset:9248
	ds_read_b128 v[106:109], v172 offset:32
	ds_read_b128 v[102:105], v172 offset:64
	s_mov_b64 s[76:77], 0
	s_waitcnt lgkmcnt(3)
	v_mfma_f32_32x32x16_bf16 v[34:49], v[50:53], v[34:37], 0
	s_waitcnt lgkmcnt(1)
	v_mfma_f32_32x32x16_bf16 v[34:49], v[106:109], v[54:57], v[34:49]
	ds_read_b128 v[54:57], v58 offset:9280
	s_waitcnt lgkmcnt(0)
	v_mfma_f32_32x32x16_bf16 v[34:49], v[102:105], v[54:57], v[34:49]
	ds_read_b128 v[110:113], v172 offset:96
	ds_read_b128 v[54:57], v58 offset:9312
	s_waitcnt lgkmcnt(0)
	v_mfma_f32_32x32x16_bf16 v[34:49], v[110:113], v[54:57], v[34:49]

; __device__ __forceinline__ void gla_unit(LAS char* lds0, int b, int h, int dvh, bf16_t* Z, bf16_t* OT, const float* afw, const float* afb, const float* abw, const float* abb, bool dry) {
;     ...
; #pragma unroll
;             for (int k = 0; k < 4; ++k) {
;                 const bf16x8 a = *(const LAS bf16x8*)(lds + G_Q + (32 * I + r32) * GP + (16 * k + 8 * hi) * 2);
;                 const LAS char* sp = lds + G_SB + (16 * k + 8 * hi + q4) * GP + (32 * J + 16 * g16 + 4 * p4) * 2;
;                 const s16x4 l0 = trread(sp), l1 = trread(sp + 4 * GP);
;                 oacc = __builtin_amdgcn_mfma_f32_32x32x16_bf16(a, MK8(l0, l1), oacc, 0, 0, 0);
;             }
; #pragma unroll
;             for (int r = 0; r < 16; ++r) { const int i_ = 32 * I + crow(r, hi), j_ = 32 * J + r32;
;                 ((LAS bf16_t*)(lds + G_AM))[i_ * (GP / 2) + j_] = f2bf((i_ >= j_) ? Ac[r] : 0.f); }
;         }
;         asm volatile("s_waitcnt lgkmcnt(0)\n\ts_barrier" ::: "memory");
;         {
; #pragma unroll
;             for (int u = 0; u < 4; ++u) {
;                 const bf16x8 a = *(const LAS bf16x8*)(lds + G_AM + (32 * I + r32) * GP + (16 * u + 8 * hi) * 2);
;                 const LAS char* vp = lds + G_V + (16 * u + 8 * hi + q4) * GP + (32 * J + 16 * g16 + 4 * p4) * 2;
;                 const s16x4 l0 = trread(vp), l1 = trread(vp + 4 * GP);
;                 oacc = __builtin_amdgcn_mfma_f32_32x32x16_bf16(a, MK8(l0, l1), oacc, 0, 0, 0);
;             }
; #pragma unroll
;             for (int r = 0; r < 16; ++r) ((LAS bf16_t*)(lds + G_O))[(32 * I + crow(r, hi)) * (GP / 2) + 32 * J + r32] = f2bf(oacc[r]);
;             const int Dd = I;
; #pragma unroll
;             for (int k = 0; k < 4; ++k) { const f32x4 dc = *(const LAS f32x4*)(lds + G_DEC + (32 * Dd + 8 * k + 4 * hi) * 4);
; #pragma unroll
;                 for (int j = 0; j < 4; ++j) S[4 * k + j] *= dc[j]; }
; #pragma unroll
;             for (int u = 0; u < 4; ++u) {
;                 const LAS char* kp = lds + G_KD + (16 * u + 8 * hi + q4) * GP + (32 * Dd + 16 * g16 + 4 * p4) * 2;
;                 const LAS char* vp = lds + G_V + (16 * u + 8 * hi + q4) * GP + (32 * J + 16 * g16 + 4 * p4) * 2;
;                 const s16x4 k0 = trread(kp), k1 = trread(kp + 4 * GP), v0 = trread(vp), v1 = trread(vp + 4 * GP);
;                 S = __builtin_amdgcn_mfma_f32_32x32x16_bf16(MK8(k0, k1), MK8(v0, v1), S, 0, 0, 0);
.LBB0_420:
	s_nop 9
	v_add_u32_e32 v173, v137, v154
	ds_read_b128 v[54:57], v239 offset:46080
	ds_read_b128 v[174:177], v239 offset:46112
	ds_read_b128 v[178:181], v239 offset:46144
	ds_read_b128 v[188:191], v239 offset:46176
	v_cndmask_b32_e64 v34, v34, 0, s[42:43]
	v_cndmask_b32_e64 v35, v35, 0, s[44:45]
	v_cndmask_b32_e64 v36, v36, 0, s[46:47]
	v_cndmask_b32_e64 v37, v37, 0, s[50:51]
	v_cvt_pk_bf16_f32 v242, v34, v35
	v_cvt_pk_bf16_f32 v243, v36, v37
	ds_write_b64 v238, v[242:243] offset:36864
	s_waitcnt lgkmcnt(4)
	v_mfma_f32_32x32x16_bf16 v[50:65], v[50:53], v[54:57], 0
	v_cndmask_b32_e64 v38, v38, 0, s[52:53]
	v_cndmask_b32_e64 v39, v39, 0, s[54:55]
	v_cndmask_b32_e64 v40, v40, 0, s[56:57]
	v_cndmask_b32_e64 v41, v41, 0, s[58:59]
	v_cvt_pk_bf16_f32 v242, v38, v39
	v_cvt_pk_bf16_f32 v243, v40, v41
	ds_write_b64 v238, v[242:243] offset:36880
	s_waitcnt lgkmcnt(4)
	v_mfma_f32_32x32x16_bf16 v[50:65], v[106:109], v[174:177], v[50:65]
	v_cndmask_b32_e64 v42, v42, 0, s[60:61]
	v_cndmask_b32_e64 v43, v43, 0, s[62:63]
	v_cndmask_b32_e64 v44, v44, 0, s[64:65]
	v_cndmask_b32_e64 v45, v45, 0, s[66:67]
	v_cvt_pk_bf16_f32 v242, v42, v43
	v_cvt_pk_bf16_f32 v243, v44, v45
	ds_write_b64 v238, v[242:243] offset:36896
	s_waitcnt lgkmcnt(4)
	v_mfma_f32_32x32x16_bf16 v[50:65], v[102:105], v[178:181], v[50:65]
	v_cndmask_b32_e64 v46, v46, 0, s[68:69]
	v_cndmask_b32_e64 v47, v47, 0, s[70:71]
	v_cndmask_b32_e64 v48, v48, 0, s[72:73]
	v_cndmask_b32_e64 v49, v49, 0, s[74:75]
	v_cvt_pk_bf16_f32 v242, v46, v47
	v_cvt_pk_bf16_f32 v243, v48, v49
	ds_write_b64 v238, v[242:243] offset:36912
	s_waitcnt lgkmcnt(4)
	v_mfma_f32_32x32x16_bf16 v[50:65], v[110:113], v[188:191], v[50:65]
	s_waitcnt lgkmcnt(0)
	s_barrier
	ds_read_b64_tr_b16 v[34:35], v166 offset:36864
	ds_read_b64_tr_b16 v[36:37], v166 offset:37440
	ds_read_b64_tr_b16 v[38:39], v173 offset:27648
	ds_read_b64_tr_b16 v[40:41], v173 offset:28224
	ds_read_b64_tr_b16 v[42:43], v166 offset:39168
	ds_read_b64_tr_b16 v[44:45], v166 offset:39744
	ds_read_b64_tr_b16 v[46:47], v157 offset:27648
	ds_read_b64_tr_b16 v[48:49], v157 offset:28224
	s_andn2_b64 vcc, exec, s[2:3]
	s_mov_b64 s[2:3], -1
	s_waitcnt lgkmcnt(4)
	v_mfma_f32_32x32x16_bf16 v[50:65], v[34:37], v[38:41], v[50:65]
	ds_read_b64_tr_b16 v[34:35], v166 offset:41472
	ds_read_b64_tr_b16 v[36:37], v166 offset:42048
	ds_read_b64_tr_b16 v[38:39], v158 offset:27648
	ds_read_b64_tr_b16 v[40:41], v158 offset:28224
	s_waitcnt lgkmcnt(4)
	v_mfma_f32_32x32x16_bf16 v[50:65], v[42:45], v[46:49], v[50:65]
	ds_read_b64_tr_b16 v[42:43], v166 offset:43776
	ds_read_b64_tr_b16 v[44:45], v166 offset:44352
	ds_read_b64_tr_b16 v[46:47], v159 offset:27648
	ds_read_b64_tr_b16 v[48:49], v159 offset:28224
	s_waitcnt lgkmcnt(4)
	v_mfma_f32_32x32x16_bf16 v[50:65], v[34:37], v[38:41], v[50:65]
	s_waitcnt lgkmcnt(0)
	v_mfma_f32_32x32x16_bf16 v[50:65], v[42:45], v[46:49], v[50:65]
	s_nop 11
	v_cvt_pk_bf16_f32 v34, v50, s0
	ds_write_b16 v161, v34 offset:55296
	v_cvt_pk_bf16_f32 v34, v51, s0
	ds_write_b16 v161, v34 offset:55440
	v_cvt_pk_bf16_f32 v34, v52, s0
	ds_write_b16 v161, v34 offset:55584
	v_cvt_pk_bf16_f32 v34, v53, s0
	ds_write_b16 v161, v34 offset:55728
	v_cvt_pk_bf16_f32 v34, v54, s0
	ds_write_b16 v161, v34 offset:56448
	v_cvt_pk_bf16_f32 v34, v55, s0
	ds_write_b16 v161, v34 offset:56592
	v_cvt_pk_bf16_f32 v34, v56, s0
	ds_write_b16 v161, v34 offset:56736
	v_cvt_pk_bf16_f32 v34, v57, s0
	ds_write_b16 v161, v34 offset:56880
	v_cvt_pk_bf16_f32 v34, v58, s0
	ds_write_b16 v161, v34 offset:57600
	v_cvt_pk_bf16_f32 v34, v59, s0
	ds_write_b16 v161, v34 offset:57744
	v_cvt_pk_bf16_f32 v34, v60, s0
	ds_write_b16 v161, v34 offset:57888
	v_cvt_pk_bf16_f32 v34, v61, s0
	ds_write_b16 v161, v34 offset:58032
	v_cvt_pk_bf16_f32 v34, v62, s0
	ds_write_b16 v161, v34 offset:58752
	v_cvt_pk_bf16_f32 v34, v63, s0
	ds_write_b16 v161, v34 offset:58896
	v_cvt_pk_bf16_f32 v34, v64, s0
	ds_write_b16 v161, v34 offset:59040
	v_cvt_pk_bf16_f32 v34, v65, s0
	ds_write_b16 v161, v34 offset:59184
	ds_read_b128 v[34:37], v165
	ds_read_b128 v[38:41], v164
	ds_read_b128 v[42:45], v163
	ds_read_b128 v[46:49], v162
	s_waitcnt lgkmcnt(3)
	v_pk_mul_f32 v[30:31], v[30:31], v[34:35]
	s_waitcnt lgkmcnt(2)
	v_pk_mul_f32 v[26:27], v[26:27], v[38:39]
	s_waitcnt lgkmcnt(1)
	v_pk_mul_f32 v[22:23], v[22:23], v[42:43]
	s_waitcnt lgkmcnt(0)
	v_pk_mul_f32 v[18:19], v[18:19], v[46:47]
	v_pk_mul_f32 v[32:33], v[32:33], v[36:37]
	v_pk_mul_f32 v[28:29], v[28:29], v[40:41]
	v_pk_mul_f32 v[24:25], v[24:25], v[44:45]
	v_pk_mul_f32 v[20:21], v[20:21], v[48:49]
	ds_read_b128 v[34:37], v172 offset:18432
	ds_read_b64_tr_b16 v[38:39], v173 offset:27648
	ds_read_b64_tr_b16 v[40:41], v173 offset:28224
	ds_read_b128 v[42:45], v172 offset:18464
	ds_read_b64_tr_b16 v[46:47], v173 offset:29952
	ds_read_b64_tr_b16 v[48:49], v173 offset:30528
	ds_read_b64_tr_b16 v[50:51], v173 offset:32256
	ds_read_b64_tr_b16 v[56:57], v173 offset:35136
	s_waitcnt lgkmcnt(5)
	v_mfma_f32_32x32x16_bf16 v[18:33], v[34:37], v[38:41], v[18:33]
	ds_read_b128 v[34:37], v172 offset:18496
	ds_read_b64_tr_b16 v[52:53], v173 offset:32832
	ds_read_b64_tr_b16 v[54:55], v173 offset:34560
	ds_read_b128 v[38:41], v172 offset:18528
	s_waitcnt lgkmcnt(0)
	s_barrier
	s_waitcnt lgkmcnt(8)
	v_mfma_f32_32x32x16_bf16 v[18:33], v[42:45], v[46:49], v[18:33]
	s_waitcnt lgkmcnt(3)
	v_mfma_f32_32x32x16_bf16 v[18:33], v[34:37], v[50:53], v[18:33]
	s_waitcnt lgkmcnt(0)
	v_mfma_f32_32x32x16_bf16 v[18:33], v[38:41], v[54:57], v[18:33]
	s_nop 11
	v_cvt_pk_bf16_f32 v242, v18, v19
	v_cvt_pk_bf16_f32 v243, v20, v21
	ds_write_b64 v238, v[242:243] offset:46080
	v_cvt_pk_bf16_f32 v242, v22, v23
	v_cvt_pk_bf16_f32 v243, v24, v25
	ds_write_b64 v238, v[242:243] offset:46096
	v_cvt_pk_bf16_f32 v242, v26, v27
	v_cvt_pk_bf16_f32 v243, v28, v29
	ds_write_b64 v238, v[242:243] offset:46112
	v_cvt_pk_bf16_f32 v242, v30, v31
	v_cvt_pk_bf16_f32 v243, v32, v33
	ds_write_b64 v238, v[242:243] offset:46128
	ds_read_b128 v[38:41], v171 offset:55296
	ds_read_b128 v[34:37], v167 offset:55296
	s_cbranch_vccnz .LBB0_422
	s_mov_b64 s[2:3], 0
